# superset: v70 + pipelined EpiResid epilogues + batched tr-read waits + pipelined mini/gz loads + GLA unit software prefetch
# speedup vs baseline: 1.0145x; 1.0071x over previous
.LBB0_608:
	s_or_b64 exec, exec, s[86:87]
	global_load_dword v254, v[230:231], off
	global_load_dword v254, v[232:233], off
	global_load_dword v254, v[234:235], off
	global_load_dword v254, v[236:237], off
	global_load_dword v254, v[238:239], off
	global_load_dword v254, v[240:241], off
	v_add_u32_e32 v0, v73, v84
	ds_write_b128 v0, v[4:7]
	v_add_u32_e32 v0, v73, v85
	ds_write_b128 v0, v[12:15]
	v_add_u32_e32 v0, v73, v86
	ds_write_b128 v0, v[8:11]
	v_add_u32_e32 v0, v73, v87
	ds_write_b128 v0, v[20:23]
	s_waitcnt lgkmcnt(0)
	s_barrier
	ds_read_b64_tr_b16 v[0:1], v88
	ds_read_b64_tr_b16 v[2:3], v89
	ds_read_b64_tr_b16 v[4:5], v90
	ds_read_b64_tr_b16 v[6:7], v91
	ds_read_b64_tr_b16 v[8:9], v92
	ds_read_b64_tr_b16 v[10:11], v93
	ds_read_b64_tr_b16 v[16:17], v94
	ds_read_b64_tr_b16 v[18:19], v95
	ds_read_b64_tr_b16 v[24:25], v96
	ds_read_b64_tr_b16 v[26:27], v97
	ds_read_b64_tr_b16 v[174:175], v98
	ds_read_b64_tr_b16 v[176:177], v99
	ds_read_b64_tr_b16 v[182:183], v100
	ds_read_b64_tr_b16 v[184:185], v101
	ds_read_b64_tr_b16 v[190:191], v102
	ds_read_b64_tr_b16 v[192:193], v103
	ds_read_b64_tr_b16 v[198:199], v104
	ds_read_b64_tr_b16 v[200:201], v105
	ds_read_b64_tr_b16 v[206:207], v106
	ds_read_b64_tr_b16 v[208:209], v107
	s_waitcnt lgkmcnt(0)
	s_nop 0
	v_mfma_f32_16x16x32_bf16 v[12:15], v[8:11], v[0:3], 0
	s_lshl_b64 s[84:85], s[84:85], 16
	s_mov_b64 s[86:87], s[38:39]
	s_add_u32 s84, s86, s84
	v_mfma_f32_16x16x32_bf16 v[8:11], v[8:11], v[4:7], 0
	s_addc_u32 s85, s87, s85
	s_add_i32 s2, s2, s88
	s_cmpk_lt_i32 s2, 0x804
	v_mfma_f32_16x16x32_bf16 v[20:23], v[16:19], v[0:3], 0
	v_mfma_f32_16x16x32_bf16 v[16:19], v[16:19], v[4:7], 0
	v_mfma_f32_16x16x32_bf16 v[170:173], v[24:27], v[0:3], 0
	v_mfma_f32_16x16x32_bf16 v[24:27], v[24:27], v[4:7], 0
	v_mfma_f32_16x16x32_bf16 v[178:181], v[174:177], v[0:3], 0
	v_mfma_f32_16x16x32_bf16 v[174:177], v[174:177], v[4:7], 0
	v_mfma_f32_16x16x32_bf16 v[186:189], v[182:185], v[0:3], 0
	v_mfma_f32_16x16x32_bf16 v[182:185], v[182:185], v[4:7], 0
	v_mfma_f32_16x16x32_bf16 v[194:197], v[190:193], v[0:3], 0
	v_mfma_f32_16x16x32_bf16 v[190:193], v[190:193], v[4:7], 0
	v_mfma_f32_16x16x32_bf16 v[202:205], v[198:201], v[0:3], 0
	v_mfma_f32_16x16x32_bf16 v[198:201], v[198:201], v[4:7], 0
	v_mfma_f32_16x16x32_bf16 v[0:3], v[206:209], v[0:3], 0
	v_mfma_f32_16x16x32_bf16 v[4:7], v[206:209], v[4:7], 0
	ds_read_b64_tr_b16 v[206:207], v108
	ds_read_b64_tr_b16 v[208:209], v109
	ds_read_b64_tr_b16 v[210:211], v110
	ds_read_b64_tr_b16 v[212:213], v111
	ds_read_b64_tr_b16 v[214:215], v112
	ds_read_b64_tr_b16 v[216:217], v113
	s_waitcnt lgkmcnt(0)
	s_nop 0
	v_mfma_f32_16x16x32_bf16 v[12:15], v[214:217], v[206:209], v[12:15]
	v_mfma_f32_16x16x32_bf16 v[8:11], v[214:217], v[210:213], v[8:11]
	ds_read_b64_tr_b16 v[214:215], v114
	ds_read_b64_tr_b16 v[216:217], v115
	s_waitcnt lgkmcnt(0)
	s_nop 0
	v_mfma_f32_16x16x32_bf16 v[20:23], v[214:217], v[206:209], v[20:23]
	v_mfma_f32_16x16x32_bf16 v[16:19], v[214:217], v[210:213], v[16:19]
	ds_read_b64_tr_b16 v[214:215], v116
	ds_read_b64_tr_b16 v[216:217], v117
	s_waitcnt lgkmcnt(0)
	s_nop 0
	v_mfma_f32_16x16x32_bf16 v[170:173], v[214:217], v[206:209], v[170:173]
	v_mfma_f32_16x16x32_bf16 v[24:27], v[214:217], v[210:213], v[24:27]
	ds_read_b64_tr_b16 v[214:215], v118
	ds_read_b64_tr_b16 v[216:217], v119
	s_waitcnt lgkmcnt(0)
	s_nop 0
	v_mfma_f32_16x16x32_bf16 v[178:181], v[214:217], v[206:209], v[178:181]
	v_mfma_f32_16x16x32_bf16 v[174:177], v[214:217], v[210:213], v[174:177]
	ds_read_b64_tr_b16 v[214:215], v120
	ds_read_b64_tr_b16 v[216:217], v121
	s_waitcnt lgkmcnt(0)
	s_nop 0
	v_mfma_f32_16x16x32_bf16 v[186:189], v[214:217], v[206:209], v[186:189]
	v_mfma_f32_16x16x32_bf16 v[182:185], v[214:217], v[210:213], v[182:185]
	ds_read_b64_tr_b16 v[214:215], v122
	ds_read_b64_tr_b16 v[216:217], v123
	s_waitcnt lgkmcnt(0)
	s_nop 0
	v_mfma_f32_16x16x32_bf16 v[194:197], v[214:217], v[206:209], v[194:197]
	v_mfma_f32_16x16x32_bf16 v[190:193], v[214:217], v[210:213], v[190:193]
	ds_read_b64_tr_b16 v[214:215], v124
	ds_read_b64_tr_b16 v[216:217], v125
	s_waitcnt lgkmcnt(0)
	s_nop 0
	v_mfma_f32_16x16x32_bf16 v[202:205], v[214:217], v[206:209], v[202:205]
	v_mfma_f32_16x16x32_bf16 v[198:201], v[214:217], v[210:213], v[198:201]
	ds_read_b64_tr_b16 v[214:215], v126
	ds_read_b64_tr_b16 v[216:217], v127
	s_waitcnt lgkmcnt(0)
	s_barrier
	v_cvt_pk_bf16_f32 v12, v12, v13
	v_cvt_pk_bf16_f32 v13, v14, v15
	ds_write_b64 v161, v[12:13]
	v_cvt_pk_bf16_f32 v8, v8, v9
	v_cvt_pk_bf16_f32 v9, v10, v11
	ds_write_b64 v161, v[8:9] offset:4352
	v_cvt_pk_bf16_f32 v8, v20, v21
	v_cvt_pk_bf16_f32 v9, v22, v23
	ds_write_b64 v161, v[8:9] offset:32
	v_cvt_pk_bf16_f32 v8, v16, v17
	v_cvt_pk_bf16_f32 v9, v18, v19
	ds_write_b64 v161, v[8:9] offset:4384
	v_cvt_pk_bf16_f32 v8, v170, v171
	v_cvt_pk_bf16_f32 v9, v172, v173
	ds_write_b64 v161, v[8:9] offset:64
	v_cvt_pk_bf16_f32 v8, v24, v25
	v_cvt_pk_bf16_f32 v9, v26, v27
	ds_write_b64 v161, v[8:9] offset:4416
	v_cvt_pk_bf16_f32 v8, v178, v179
	v_cvt_pk_bf16_f32 v9, v180, v181
	ds_write_b64 v161, v[8:9] offset:96
	v_cvt_pk_bf16_f32 v8, v174, v175
	v_cvt_pk_bf16_f32 v9, v176, v177
	ds_write_b64 v161, v[8:9] offset:4448
	v_cvt_pk_bf16_f32 v8, v186, v187
	v_cvt_pk_bf16_f32 v9, v188, v189
	ds_write_b64 v161, v[8:9] offset:128
	v_cvt_pk_bf16_f32 v8, v182, v183
	v_cvt_pk_bf16_f32 v9, v184, v185
	ds_write_b64 v161, v[8:9] offset:4480
	v_cvt_pk_bf16_f32 v8, v194, v195
	v_cvt_pk_bf16_f32 v9, v196, v197
	ds_write_b64 v161, v[8:9] offset:160
	v_cvt_pk_bf16_f32 v8, v190, v191
	v_cvt_pk_bf16_f32 v9, v192, v193
	v_mfma_f32_16x16x32_bf16 v[0:3], v[214:217], v[206:209], v[0:3]
	ds_write_b64 v161, v[8:9] offset:4512
	v_cvt_pk_bf16_f32 v8, v202, v203
	v_cvt_pk_bf16_f32 v9, v204, v205
	ds_write_b64 v161, v[8:9] offset:192
	v_cvt_pk_bf16_f32 v8, v198, v199
	v_cvt_pk_bf16_f32 v9, v200, v201
	ds_write_b64 v161, v[8:9] offset:4544
	v_cvt_pk_bf16_f32 v0, v0, v1
	v_cvt_pk_bf16_f32 v1, v2, v3
	v_mfma_f32_16x16x32_bf16 v[4:7], v[214:217], v[210:213], v[4:7]
	s_nop 3
	ds_write_b64 v161, v[0:1] offset:224
	v_cvt_pk_bf16_f32 v0, v4, v5
	v_cvt_pk_bf16_f32 v1, v6, v7
	ds_write_b64 v161, v[0:1] offset:4576
	s_waitcnt lgkmcnt(0)
	s_barrier
	v_lshl_add_u64 v[4:5], s[84:85], 0, v[36:37]
	ds_read_b128 v[0:3], v169
	s_waitcnt lgkmcnt(0)
	global_store_dwordx4 v[4:5], v[0:3], off sc1
	s_nop 1
	v_lshl_add_u64 v[4:5], s[84:85], 0, v[46:47]
	ds_read_b128 v[0:3], v162
	s_waitcnt lgkmcnt(0)
	global_store_dwordx4 v[4:5], v[0:3], off sc1
	s_nop 1
	v_lshl_add_u64 v[4:5], s[84:85], 0, v[48:49]
	ds_read_b128 v[0:3], v163
	s_waitcnt lgkmcnt(0)
	global_store_dwordx4 v[4:5], v[0:3], off sc1
	s_nop 1
	v_lshl_add_u64 v[4:5], s[84:85], 0, v[50:51]
	ds_read_b128 v[0:3], v164
	s_waitcnt lgkmcnt(0)
	global_store_dwordx4 v[4:5], v[0:3], off sc1
	s_nop 1
	v_lshl_add_u64 v[4:5], s[84:85], 0, v[52:53]
	ds_read_b128 v[0:3], v165
	s_waitcnt lgkmcnt(0)
	global_store_dwordx4 v[4:5], v[0:3], off sc1
	s_nop 1
	v_lshl_add_u64 v[4:5], s[84:85], 0, v[54:55]
	ds_read_b128 v[0:3], v166
	s_waitcnt lgkmcnt(0)
	global_store_dwordx4 v[4:5], v[0:3], off sc1
	s_nop 1
	v_lshl_add_u64 v[4:5], s[84:85], 0, v[56:57]
	ds_read_b128 v[0:3], v167
	s_waitcnt lgkmcnt(0)
	global_store_dwordx4 v[4:5], v[0:3], off sc1
	s_nop 1
	v_lshl_add_u64 v[4:5], s[84:85], 0, v[58:59]
	ds_read_b128 v[0:3], v168
	s_waitcnt lgkmcnt(0)
	global_store_dwordx4 v[4:5], v[0:3], off sc1
	s_nop 1
	s_barrier
	s_cbranch_scc0 .LBB0_641
